# far-tile body: workgroup barrier behind K.Q^T, next tile K fragments read during the P.V tail
# baseline (speedup 1.0000x reference)
; template <bool DIFF> DI void attn_unit(LAS unsigned char* L, const bf16* Qh, int qpitch, const bf16* Kh, const bf16* Vh, int kvpitch, bf16* Oh, int opitch, ...
;     ...
;     const int koff = ((r * KP) + kcol + 8 * h_) * 2;
;     const int voff = 2 * KSLOT + ((4 * h_ + q_) * VP + 16 * g_ + 4 * p_) * 2;
;     bf16x8 pf[2][2]; bool pa0 = false, pa1 = false;
; #pragma unroll
;     for (int a = 0; a < 2; ++a)
; #pragma unroll
;         for (int b = 0; b < 2; ++b) pf[a][b] = (bf16x8){0, 0, 0, 0, 0, 0, 0, 0};
;     int vcur = 0, vprev = 2;
;     const int qbase = qpos0 + wq0, qlast = qbase + 31;
;     for (int t = 0; t < NT; ++t) {
.LBB0_190:
	s_lshl_b32 s8, s68, 11
	s_and_b32 s9, s10, 7
	s_and_b32 s8, s8, 0x1800000
	s_lshl_b32 s9, s9, 8
	s_add_i32 s84, s63, s25
	s_mov_b32 s25, s37
	s_lshl_b32 s86, s24, 1
	s_or_b32 s36, s8, s9
	s_lshl_b64 s[8:9], s[24:25], 18
	s_or_b32 s81, s1, 31
	s_mov_b32 s94, 1
	s_mov_b32 s87, 2
	s_add_i32 s93, s86, 2
	v_lshl_add_u64 v[198:199], v[194:195], 0, s[36:37]
	s_or_b32 s24, s8, 0x20000
	s_mov_b32 s9, 0
	s_mov_b64 s[10:11], 0
	s_mov_b32 s25, 64
	s_waitcnt lgkmcnt(0)
	s_barrier
	s_mov_b32 s100, 0

; template <bool DIFF> DI void attn_unit(LAS unsigned char* L, const bf16* Qh, int qpitch, const bf16* Kh, const bf16* Vh, int kvpitch, bf16* Oh, int opitch, ...
;     ...
;         if (stag && pa0) att_pv(L + voff + vprev * VSLOT, pf, y, pa1);
.Lhead_nf:
	s_and_b64 s[28:29], s[16:17], s[28:29]
	s_andn2_b64 vcc, exec, s[28:29]
	s_cbranch_vccnz .LBB0_199

; #define LAS __attribute__((address_space(3)))
; DI float xmax32(float v) { auto rr = __builtin_amdgcn_permlane32_swap(__float_as_uint(v), __float_as_uint(v), false, false); return fmaxf(__uint_as_float(rr[0]), __uint_as_float(rr[1])); }
; template <bool DIFF, int ND0> DI void att_qk_softmax(const LAS unsigned char* Kc, const bf16x8 (&qf)[ND0], const LAS float* tbl, int t, int qbase, int r, int h_, bool act1, ...
;     ...
;     for (int sub = 0; sub < 2; ++sub) {
;         p[sub] = negm;
;         if (sub == 0 || act1) {
; #pragma unroll
;             for (int d0 = 0; d0 < ND0; ++d0) { const bf16x8 kf = *(const LAS bf16x8*)(Kc + (32 * sub * ATT_KP + 16 * d0) * 2);
;                 p[sub] = __builtin_amdgcn_mfma_f32_32x32x16_bf16(kf, qf[d0], p[sub], 0, 0, 0); }
;         }
;     }
;     const bool far = !DIFF || (qbase - (64 * t + 63) >= 128);
;     if (!far) {
;         const int qpos = qbase + r;
; #pragma unroll
;         for (int sub = 0; sub < 2; ++sub)
; #pragma unroll
;             for (int i = 0; i < 16; ++i) { const int dist = qpos - (64 * t + 32 * sub + crow(i, h_));
;                 const int idx = dist < 0 ? 0 : (dist > 255 ? 255 : dist); float s = p[sub][i] + tbl[idx]; s = dist >= 0 ? s : -INFINITY;
;                 if (sub == 1 && !act1) s = -INFINITY;
;                 p[sub][i] = s; }
;     }
;     float mx = -INFINITY;
; #pragma unroll
;     for (int sub = 0; sub < 2; ++sub)
; #pragma unroll
;         for (int i = 0; i < 16; ++i) mx = fmaxf(mx, p[sub][i]);
;     mx = xmax32(mx);
; template <bool DIFF> DI void attn_unit(LAS unsigned char* L, const bf16* Qh, int qpitch, const bf16* Kh, const bf16* Vh, int kvpitch, bf16* Oh, int opitch, ...
;     ...
;     for (int t = 0; t < NT; ++t) {
;         const int cur = t & 1, vnext = (vcur == 2) ? 0 : vcur + 1;
;         if (t + 1 < NT) ATT_STORE(cur ^ 1, vnext);
;         if (t + 2 < NT) ATT_LOAD(t + 2);
;         const LAS unsigned char* Kc = L + cur * KSLOT + koff;
;         const bool act0 = !DIFF || (64 * t <= qlast), act1 = !DIFF || (64 * t + 32 <= qlast);
;         if (stag && pa0) att_pv(L + voff + vprev * VSLOT, pf, y, pa1);
;         if (act0) att_qk_softmax<DIFF, ND0>(Kc, qf, tbl, t, qbase, r, h_, act1, m_run, l_run, negm, y, pf);
;         if (!stag && act0) att_pv(L + voff + vcur * VSLOT, pf, y, act1);
;         pa0 = act0; pa1 = act1;
;         vprev = vcur; vcur = vnext;
;         __syncthreads();
.LBB0_210:
.LBB0_211:
	s_add_u32 s10, s10, 0x20000
	s_addc_u32 s11, s11, 0
	s_add_i32 s87, s87, 1
	s_sub_i32 s84, s84, 64
	s_add_i32 s25, s25, 64
	s_waitcnt lgkmcnt(0)
	s_cmp_lg_u32 s100, 0
	s_cbranch_scc1 .Lskip_bar
	s_barrier
.Lskip_bar:
	s_mov_b32 s100, 0
	s_cmp_eq_u32 s24, s10
	s_cbranch_scc1 .LBB0_213
	s_mov_b32 s9, s95
	s_branch .LBB0_191
.Lfast:
	s_mulk_i32 s8, 0x4400
	v_add_u32_e32 v221, s8, v216
	ds_read_b128 v[96:99], v221
	ds_read_b128 v[100:103], v221 offset:32
	ds_read_b128 v[104:107], v221 offset:64
	ds_read_b128 v[108:111], v221 offset:96
	ds_read_b128 v[222:225], v221 offset:8704
	ds_read_b128 v[226:229], v221 offset:8736
	ds_read_b128 v[244:247], v221 offset:8768
	ds_read_b128 v[248:251], v221 offset:8800
.Lfast2:
	s_and_b32 s36, s96, 1
	s_xor_b32 s36, s36, 1
	s_mulk_i32 s36, 0x4400
	s_mul_i32 s85, s94, 0x5000
	s_waitcnt lgkmcnt(0)
	v_mfma_f32_32x32x16_bf16 v[80:95], v[96:99], v[112:115], v[64:79]
	v_add_u32_e32 v239, s36, v210
	s_waitcnt vmcnt(3)
	ds_write_b128 v239, v[128:131]
	v_mfma_f32_32x32x16_bf16 v[80:95], v[100:103], v[116:119], v[80:95]
	v_add_u32_e32 v239, s85, v211
	s_waitcnt vmcnt(2)
	ds_write_b128 v239, v[132:135] offset:34816
	v_mfma_f32_32x32x16_bf16 v[80:95], v[104:107], v[120:123], v[80:95]
	v_add_u32_e32 v239, s36, v212
	s_waitcnt vmcnt(1)
	ds_write_b128 v239, v[136:139]
	v_mfma_f32_32x32x16_bf16 v[80:95], v[108:111], v[124:127], v[80:95]
	v_add_u32_e32 v239, s85, v213
	s_waitcnt vmcnt(0)
	ds_write_b128 v239, v[140:143] offset:34816
	v_mfma_f32_32x32x16_bf16 v[96:111], v[222:225], v[112:115], v[64:79]
	v_lshl_add_u64 v[240:241], v[198:199], 0, s[10:11]
	v_add_co_u32_e32 v242, vcc, 0x13060000, v240
	s_nop 1
	v_addc_co_u32_e32 v243, vcc, 0, v241, vcc
	v_add_co_u32_e32 v238, vcc, 0x15060000, v240
	s_nop 1
	v_addc_co_u32_e32 v239, vcc, 0, v241, vcc
	v_mfma_f32_32x32x16_bf16 v[96:111], v[226:229], v[116:119], v[96:111]
	global_load_dwordx4 v[128:131], v[242:243], off
	global_load_dwordx4 v[132:135], v[238:239], off
	v_add_co_u32_e32 v242, vcc, 0x13070000, v240
	s_nop 1
	v_addc_co_u32_e32 v243, vcc, 0, v241, vcc
	v_add_co_u32_e32 v238, vcc, 0x15070000, v240
	s_nop 1
	v_addc_co_u32_e32 v239, vcc, 0, v241, vcc
	v_mfma_f32_32x32x16_bf16 v[96:111], v[244:247], v[120:123], v[96:111]
	global_load_dwordx4 v[136:139], v[242:243], off
	global_load_dwordx4 v[140:143], v[238:239], off
	v_max3_f32 v208, v80, s3, v81
	v_max3_f32 v208, v208, v82, v83
	v_max3_f32 v208, v208, v84, v85
	v_max3_f32 v208, v208, v86, v87
	v_max3_f32 v208, v208, v88, v89
	v_max3_f32 v208, v208, v90, v91
	v_max3_f32 v208, v208, v92, v93
	v_max3_f32 v208, v208, v94, v95
	v_mfma_f32_32x32x16_bf16 v[96:111], v[248:251], v[124:127], v[96:111]
	s_mul_i32 s8, s95, 0x5000
	v_add_u32_e32 v238, s8, v217
	ds_read_b64_tr_b16 v[240:241], v238 offset:34816
	ds_read_b64_tr_b16 v[242:243], v238 offset:37376
	s_waitcnt lgkmcnt(2)
	s_barrier
	s_nop 5
	v_max3_f32 v208, v208, v96, v97
	v_max3_f32 v208, v208, v98, v99
	v_max3_f32 v208, v208, v100, v101
	v_max3_f32 v208, v208, v102, v103
	v_max3_f32 v208, v208, v104, v105
	v_max3_f32 v208, v208, v106, v107
	v_max3_f32 v208, v208, v108, v109
	v_max3_f32 v208, v208, v110, v111
	v_mov_b32_e32 v221, v208
	s_nop 1
	v_permlane32_swap_b32_e32 v208, v221
	v_max_f32_e32 v221, v221, v221
	v_max_f32_e32 v208, v208, v208
	v_max_f32_e32 v221, v208, v221
	v_cmp_lt_f32_e32 vcc, s92, v221
	s_cbranch_vccnz .Lfast_resc
; template <bool DIFF, int ND0> DI void att_qk_softmax(const LAS unsigned char* Kc, const bf16x8 (&qf)[ND0], const LAS float* tbl, int t, int qbase, int r, int h_, bool act1, ...
;     ...
;     float rs = 0.f;
; #pragma unroll
;     for (int sub = 0; sub < 2; ++sub)
; #pragma unroll
;         for (int i = 0; i < 16; ++i) { const float e = __builtin_amdgcn_exp2f(p[sub][i]); p[sub][i] = e; rs += e; }
;     l_run += rs;
; #pragma unroll
;     for (int sub = 0; sub < 2; ++sub)
; #pragma unroll
;         for (int s = 0; s < 2; ++s) { u32x4 pw; pw.x = pk2(p[sub][8 * s], p[sub][8 * s + 1]); pw.y = pk2(p[sub][8 * s + 2], p[sub][8 * s + 3]); pw.z = pk2(p[sub][8 * s + 4], p[sub][8 * s + 5]); pw.w = pk2(p[sub][8 * s + 6], p[sub][8 * s + 7]);
;             pf[sub][s] = __builtin_bit_cast(bf16x8, pw); }
; }
; DI void att_pv(const LAS unsigned char* Vc, const bf16x8 (&pf)[2][2], f32x16 (&y)[4], bool act1) {
; #pragma unroll
;     for (int sub = 0; sub < 2; ++sub) {
;         if (sub == 0 || act1) {
; #pragma unroll
;             for (int s = 0; s < 2; ++s) {
;             __builtin_amdgcn_sched_barrier(0);
; #pragma unroll
;                 for (int d0 = 0; d0 < 4; ++d0) { const LAS unsigned char* vp = Vc + ((32 * sub + 16 * s) * ATT_VP + 32 * d0) * 2;
;                     const s16x4 lo = __builtin_bit_cast(s16x4, __builtin_amdgcn_ds_read_tr16_b64_v4i16((LAS v4i16_t*)vp));
;                     const s16x4 hi = __builtin_bit_cast(s16x4, __builtin_amdgcn_ds_read_tr16_b64_v4i16((LAS v4i16_t*)(vp + 8 * ATT_VP * 2)));
;                     const bf16x8 vf = __builtin_shufflevector(lo, hi, 0, 1, 2, 3, 4, 5, 6, 7);
;                     y[d0] = __builtin_amdgcn_mfma_f32_32x32x16_bf16(vf, pf[sub][s], y[d0], 0, 0, 0); }
;             }
;         }
;     }
;     __builtin_amdgcn_sched_barrier(0);
; }
; template <bool DIFF> DI void attn_unit(LAS unsigned char* L, const bf16* Qh, int qpitch, const bf16* Kh, const bf16* Vh, int kvpitch, bf16* Oh, int opitch, ...
;     ...
;     for (int t = 0; t < NT; ++t) {
;         const int cur = t & 1, vnext = (vcur == 2) ? 0 : vcur + 1;
;         if (t + 1 < NT) ATT_STORE(cur ^ 1, vnext);
;         if (t + 2 < NT) ATT_LOAD(t + 2);
;         const LAS unsigned char* Kc = L + cur * KSLOT + koff;
;         const bool act0 = !DIFF || (64 * t <= qlast), act1 = !DIFF || (64 * t + 32 <= qlast);
;         if (stag && pa0) att_pv(L + voff + vprev * VSLOT, pf, y, pa1);
	v_exp_f32_e32 v80, v80
	v_exp_f32_e32 v81, v81
	v_exp_f32_e32 v82, v82
	v_exp_f32_e32 v83, v83
	v_add_f32_e32 v208, 0, v80
	v_exp_f32_e32 v84, v84
	v_add_f32_e32 v208, v81, v208
	v_exp_f32_e32 v85, v85
	v_add_f32_e32 v208, v82, v208
	v_exp_f32_e32 v86, v86
	v_add_f32_e32 v208, v83, v208
	v_exp_f32_e32 v87, v87
	v_add_f32_e32 v208, v84, v208
	v_exp_f32_e32 v88, v88
	v_add_f32_e32 v208, v85, v208
	v_exp_f32_e32 v89, v89
	v_add_f32_e32 v208, v86, v208
	v_exp_f32_e32 v90, v90
	v_add_f32_e32 v208, v87, v208
	v_exp_f32_e32 v91, v91
	v_add_f32_e32 v208, v88, v208
	v_exp_f32_e32 v92, v92
	v_add_f32_e32 v208, v89, v208
	v_exp_f32_e32 v93, v93
	v_add_f32_e32 v208, v90, v208
	v_exp_f32_e32 v94, v94
	v_add_f32_e32 v208, v91, v208
	v_exp_f32_e32 v95, v95
	v_add_f32_e32 v208, v92, v208
	v_add_f32_e32 v208, v93, v208
	v_add_f32_e32 v208, v94, v208
	v_add_f32_e32 v208, v95, v208
	v_cvt_pk_bf16_f32 v222, v80, v81
	v_cvt_pk_bf16_f32 v223, v82, v83
	v_cvt_pk_bf16_f32 v224, v84, v85
	v_cvt_pk_bf16_f32 v225, v86, v87
	v_cvt_pk_bf16_f32 v226, v88, v89
	v_cvt_pk_bf16_f32 v227, v90, v91
	v_cvt_pk_bf16_f32 v228, v92, v93
	v_cvt_pk_bf16_f32 v229, v94, v95
	ds_read_b64_tr_b16 v[82:83], v238 offset:34880
	ds_read_b64_tr_b16 v[84:85], v238 offset:37440
	ds_read_b64_tr_b16 v[86:87], v238 offset:34944
	ds_read_b64_tr_b16 v[88:89], v238 offset:37504
	ds_read_b64_tr_b16 v[90:91], v238 offset:35008
	ds_read_b64_tr_b16 v[92:93], v238 offset:37568
	s_waitcnt lgkmcnt(6)
	v_mfma_f32_32x32x16_bf16 v[0:15], v[240:243], v[222:225], v[0:15]
	ds_read_b64_tr_b16 v[240:241], v238 offset:39936
	ds_read_b64_tr_b16 v[242:243], v238 offset:42496
	v_exp_f32_e32 v96, v96
	v_exp_f32_e32 v97, v97
	v_add_f32_e32 v208, v96, v208
	v_add_f32_e32 v208, v97, v208
	v_cvt_pk_bf16_f32 v230, v96, v97
	s_waitcnt lgkmcnt(6)
	v_mfma_f32_32x32x16_bf16 v[32:47], v[82:85], v[222:225], v[32:47]
	ds_read_b64_tr_b16 v[82:83], v238 offset:40000
	ds_read_b64_tr_b16 v[84:85], v238 offset:42560
	v_exp_f32_e32 v98, v98
	v_exp_f32_e32 v99, v99
	v_add_f32_e32 v208, v98, v208
	v_add_f32_e32 v208, v99, v208
	v_cvt_pk_bf16_f32 v231, v98, v99
	s_waitcnt lgkmcnt(6)
	v_mfma_f32_32x32x16_bf16 v[16:31], v[86:89], v[222:225], v[16:31]
	ds_read_b64_tr_b16 v[86:87], v238 offset:40064
	ds_read_b64_tr_b16 v[88:89], v238 offset:42624
	v_exp_f32_e32 v100, v100
	v_exp_f32_e32 v101, v101
	v_add_f32_e32 v208, v100, v208
	v_add_f32_e32 v208, v101, v208
	v_cvt_pk_bf16_f32 v232, v100, v101
	s_waitcnt lgkmcnt(6)
	v_mfma_f32_32x32x16_bf16 v[48:63], v[90:93], v[222:225], v[48:63]
	ds_read_b64_tr_b16 v[90:91], v238 offset:40128
	ds_read_b64_tr_b16 v[92:93], v238 offset:42688
	v_exp_f32_e32 v102, v102
	v_exp_f32_e32 v103, v103
	v_add_f32_e32 v208, v102, v208
	v_add_f32_e32 v208, v103, v208
	v_cvt_pk_bf16_f32 v233, v102, v103
	s_waitcnt lgkmcnt(6)
	v_mfma_f32_32x32x16_bf16 v[0:15], v[240:243], v[226:229], v[0:15]
	ds_read_b64_tr_b16 v[240:241], v238 offset:45056
	ds_read_b64_tr_b16 v[242:243], v238 offset:47616
	v_exp_f32_e32 v104, v104
	v_exp_f32_e32 v105, v105
	v_add_f32_e32 v208, v104, v208
	v_add_f32_e32 v208, v105, v208
	v_cvt_pk_bf16_f32 v234, v104, v105
	s_waitcnt lgkmcnt(6)
	v_mfma_f32_32x32x16_bf16 v[32:47], v[82:85], v[226:229], v[32:47]
	ds_read_b64_tr_b16 v[82:83], v238 offset:45120
	ds_read_b64_tr_b16 v[84:85], v238 offset:47680
	v_exp_f32_e32 v106, v106
	v_exp_f32_e32 v107, v107
	v_add_f32_e32 v208, v106, v208
	v_add_f32_e32 v208, v107, v208
	v_cvt_pk_bf16_f32 v235, v106, v107
	s_waitcnt lgkmcnt(6)
	v_mfma_f32_32x32x16_bf16 v[16:31], v[86:89], v[226:229], v[16:31]
	ds_read_b64_tr_b16 v[86:87], v238 offset:45184
	ds_read_b64_tr_b16 v[88:89], v238 offset:47744
	v_exp_f32_e32 v108, v108
	v_exp_f32_e32 v109, v109
	v_add_f32_e32 v208, v108, v208
	v_add_f32_e32 v208, v109, v208
	v_cvt_pk_bf16_f32 v236, v108, v109
	s_waitcnt lgkmcnt(6)
	v_mfma_f32_32x32x16_bf16 v[48:63], v[90:93], v[226:229], v[48:63]
	ds_read_b64_tr_b16 v[90:91], v238 offset:45248
	ds_read_b64_tr_b16 v[92:93], v238 offset:47808
	v_exp_f32_e32 v110, v110
	v_exp_f32_e32 v111, v111
	v_add_f32_e32 v208, v110, v208
	v_add_f32_e32 v208, v111, v208
	v_cvt_pk_bf16_f32 v237, v110, v111
	s_waitcnt lgkmcnt(6)
	v_mfma_f32_32x32x16_bf16 v[0:15], v[240:243], v[230:233], v[0:15]
	ds_read_b64_tr_b16 v[240:241], v238 offset:50176
	ds_read_b64_tr_b16 v[242:243], v238 offset:52736
	v_add_f32_e32 v197, v197, v208
	s_waitcnt lgkmcnt(6)
	v_mfma_f32_32x32x16_bf16 v[32:47], v[82:85], v[230:233], v[32:47]
	ds_read_b64_tr_b16 v[82:83], v238 offset:50240
	ds_read_b64_tr_b16 v[84:85], v238 offset:52800
	s_waitcnt lgkmcnt(6)
	v_mfma_f32_32x32x16_bf16 v[16:31], v[86:89], v[230:233], v[16:31]
	ds_read_b64_tr_b16 v[86:87], v238 offset:50304
	ds_read_b64_tr_b16 v[88:89], v238 offset:52864
	s_waitcnt lgkmcnt(6)
	v_mfma_f32_32x32x16_bf16 v[48:63], v[90:93], v[230:233], v[48:63]
	ds_read_b64_tr_b16 v[90:91], v238 offset:50368
	ds_read_b64_tr_b16 v[92:93], v238 offset:52928
	v_add_u32_e32 v221, s36, v216
	ds_read_b128 v[96:99], v221
	ds_read_b128 v[100:103], v221 offset:32
	ds_read_b128 v[104:107], v221 offset:64
	ds_read_b128 v[108:111], v221 offset:96
	ds_read_b128 v[222:225], v221 offset:8704
	ds_read_b128 v[226:229], v221 offset:8736
	ds_read_b128 v[244:247], v221 offset:8768
	ds_read_b128 v[248:251], v221 offset:8800
	s_waitcnt lgkmcnt(14)
	v_mfma_f32_32x32x16_bf16 v[0:15], v[240:243], v[234:237], v[0:15]
	s_waitcnt lgkmcnt(12)
	v_mfma_f32_32x32x16_bf16 v[32:47], v[82:85], v[234:237], v[32:47]
	s_waitcnt lgkmcnt(10)
	v_mfma_f32_32x32x16_bf16 v[16:31], v[86:89], v[234:237], v[16:31]
	s_waitcnt lgkmcnt(8)
	v_mfma_f32_32x32x16_bf16 v[48:63], v[90:93], v[234:237], v[48:63]
	s_add_u32 s10, s10, 0x20000
	s_addc_u32 s11, s11, 0
	s_add_i32 s87, s87, 1
	s_sub_i32 s84, s84, 64
	s_add_i32 s25, s25, 64
	s_mov_b32 s9, s95
	s_add_i32 s96, s87, -1
	s_and_b32 s8, s96, 1
	s_add_i32 s36, s94, 1
	s_cmp_lg_u32 s94, 2
	s_mov_b32 s95, s94
	s_cselect_b32 s94, s36, 0
	s_cmpk_gt_i32 s84, 0x7f
	s_cbranch_scc1 .Lfast2
	s_branch .Lhead_nf
.Lfast_resc:
	s_mov_b64 s[28:29], -1
	s_mov_b64 s[26:27], -1
	v_mov_b32_e32 v220, 1
	s_mov_b32 s100, 1
	s_branch .LBB0_204

; __global__ void __launch_bounds__(512, 2) mega_fwd(Params P) {
	.amdhsa_kernel _Z8mega_fwd6Params
		.amdhsa_group_segment_fixed_size 0
		.amdhsa_private_segment_fixed_size 0
		.amdhsa_kernarg_size 464
		.amdhsa_user_sgpr_count 2
		.amdhsa_user_sgpr_dispatch_ptr 0
		.amdhsa_user_sgpr_queue_ptr 0
		.amdhsa_user_sgpr_kernarg_segment_ptr 1
		.amdhsa_user_sgpr_dispatch_id 0
		.amdhsa_user_sgpr_kernarg_preload_length 0
		.amdhsa_user_sgpr_kernarg_preload_offset 0
		.amdhsa_user_sgpr_private_segment_size 0
		.amdhsa_uses_dynamic_stack 0
		.amdhsa_enable_private_segment 0
		.amdhsa_system_sgpr_workgroup_id_x 1
		.amdhsa_system_sgpr_workgroup_id_y 0
		.amdhsa_system_sgpr_workgroup_id_z 0
		.amdhsa_system_sgpr_workgroup_info 0
		.amdhsa_system_vgpr_workitem_id 2
		.amdhsa_next_free_vgpr 256
		.amdhsa_next_free_sgpr 102
		.amdhsa_accum_offset 256
		.amdhsa_reserve_vcc 1
		.amdhsa_float_round_mode_32 0
		.amdhsa_float_round_mode_16_64 0
		.amdhsa_float_denorm_mode_32 3
		.amdhsa_float_denorm_mode_16_64 3
		.amdhsa_dx10_clamp 1
		.amdhsa_ieee_mode 1
		.amdhsa_fp16_overflow 0
		.amdhsa_tg_split 0
		.amdhsa_exception_fp_ieee_invalid_op 0
		.amdhsa_exception_fp_denorm_src 0
		.amdhsa_exception_fp_ieee_div_zero 0
		.amdhsa_exception_fp_ieee_overflow 0
		.amdhsa_exception_fp_ieee_underflow 0
		.amdhsa_exception_fp_ieee_inexact 0
		.amdhsa_exception_int_div_zero 0
	.end_amdhsa_kernel

; __global__ void __launch_bounds__(512, 2) mega_fwd(Params P) {
amdhsa.kernels:
  - .agpr_count:     0
    .args:
      - .offset:         0
        .size:           208
        .value_kind:     by_value
      - .offset:         208
        .size:           4
        .value_kind:     hidden_block_count_x
      - .offset:         212
        .size:           4
        .value_kind:     hidden_block_count_y
      - .offset:         216
        .size:           4
        .value_kind:     hidden_block_count_z
      - .offset:         220
        .size:           2
        .value_kind:     hidden_group_size_x
      - .offset:         222
        .size:           2
        .value_kind:     hidden_group_size_y
      - .offset:         224
        .size:           2
        .value_kind:     hidden_group_size_z
      - .offset:         226
        .size:           2
        .value_kind:     hidden_remainder_x
      - .offset:         228
        .size:           2
        .value_kind:     hidden_remainder_y
      - .offset:         230
        .size:           2
        .value_kind:     hidden_remainder_z
      - .offset:         248
        .size:           8
        .value_kind:     hidden_global_offset_x
      - .offset:         256
        .size:           8
        .value_kind:     hidden_global_offset_y
      - .offset:         264
        .size:           8
        .value_kind:     hidden_global_offset_z
      - .offset:         272
        .size:           2
        .value_kind:     hidden_grid_dims
      - .offset:         296
        .size:           8
        .value_kind:     hidden_multigrid_sync_arg
      - .offset:         328
        .size:           4
        .value_kind:     hidden_dynamic_lds_size
    .group_segment_fixed_size: 0
    .kernarg_segment_align: 8
    .kernarg_segment_size: 464
    .language:       OpenCL C
    .language_version:
      - 2
      - 0
    .max_flat_workgroup_size: 512
    .name:           _Z8mega_fwd6Params
    .private_segment_fixed_size: 0
    .sgpr_count:     108
    .sgpr_spill_count: 203
    .symbol:         _Z8mega_fwd6Params.kd
    .uniform_work_group_size: 1
    .uses_dynamic_stack: false
    .vgpr_count:     256
    .vgpr_spill_count: 0
    .wavefront_size: 64
